# out-proj resid as 256x128 double tiles with its own batched residual epilogue (layer 0 reads x_prompt)
# speedup vs baseline: 1.0144x; 1.0117x over previous
.LBB0_2100:
	v_readlane_b32 s2, v249, 52
	s_lshl_b32 s72, s2, 10
	s_lshl_b64 s[4:5], s[72:73], 10
	s_lshl_b32 s18, s14, 3
	s_cmp_ge_i32 s16, s18
	v_readlane_b32 s3, v249, 53
	s_cbranch_scc1 .LBB0_2211
	s_lshr_b32 s19, s14, 3
	s_lshl_b64 s[2:3], s[4:5], 1
	s_waitcnt lgkmcnt(0)
	s_add_u32 s20, s0, s2
	v_and_b32_e32 v2, 15, v0
	v_ashrrev_i32_e32 v3, 1, v0
	s_movk_i32 s2, 0xffc0
	s_addc_u32 s21, s1, s3
	v_and_or_b32 v80, v3, s2, v2
	v_readlane_b32 s2, v249, 52
	v_readlane_b32 s3, v249, 53
	s_cmp_lt_i32 s15, 0
	s_mov_b32 s3, s73
	s_cselect_b64 s[10:11], -1, 0
	v_lshrrev_b32_e32 v2, 2, v0
	s_mov_b32 s12, s2
	s_lshl_b64 s[2:3], s[2:3], 21
	v_and_b32_e32 v2, 12, v2
	v_writelane_b32 v249, s12, 52
	s_add_u32 s22, s0, s2
	v_and_or_b32 v81, v0, 64, v2
	v_writelane_b32 v249, s13, 53
	s_addc_u32 s23, s1, s3
	v_readlane_b32 s24, v249, 1
	s_nop 0
	s_cmpk_lg_u32 s24, 0x200
	s_cbranch_scc1 .LBB0_2104
	s_load_dwordx2 s[38:39], s[84:85], 0x130
	s_load_dwordx2 s[48:49], s[84:85], 0x0
	v_readlane_b32 s24, v249, 0
	s_nop 0
	s_and_b32 s25, s24, 7
	s_lshr_b32 s24, s24, 3
	s_and_b32 s27, s24, 7
	s_lshr_b32 s24, s24, 3
	s_and_b32 s28, s24, 3
	s_lshr_b32 s24, s24, 2
	s_lshl_b32 s24, s24, 3
	s_add_i32 s24, s24, s28
	s_lshl_b32 s24, s24, 3
	s_add_i32 s28, s24, s25
	s_add_i32 s29, s28, 32
	s_mul_i32 s24, s28, 0x40000
	s_add_u32 s30, s8, s24
	s_addc_u32 s31, s9, 0
	s_mul_i32 s24, s29, 0x40000
	s_add_u32 s44, s8, s24
	s_addc_u32 s45, s9, 0
	s_mul_i32 s24, s27, 0x40000
	s_add_u32 s34, s22, s24
	s_addc_u32 s35, s23, 0
	s_waitcnt lgkmcnt(0)
	s_lshl_b32 s27, s27, 9
	s_lshl_b32 s24, s28, 19
	s_add_i32 s24, s24, s27
	s_add_u32 s40, s38, s24
	s_addc_u32 s41, s39, 0
	s_lshl_b32 s24, s29, 19
	s_add_i32 s24, s24, s27
	s_add_u32 s42, s38, s24
	s_addc_u32 s43, s39, 0
	v_readlane_b32 s25, v249, 52
	s_nop 0
	s_cmp_eq_u32 s25, 0
	s_cselect_b32 s48, s48, s38
	s_cselect_b32 s49, s49, s39
	s_sub_u32 s25, s40, s38
	s_add_u32 s50, s48, s25
	s_addc_u32 s51, s49, 0
	s_add_u32 s52, s48, s24
	s_addc_u32 s53, s49, 0
	v_and_b32_e32 v144, 7, v196
	v_bfe_u32 v145, v196, 4, 2
	v_bfe_u32 v146, v196, 6, 1
	v_lshl_or_b32 v147, v146, 2, v145
	v_xor_b32_e32 v144, v144, v147
	v_lshrrev_b32_e32 v147, 3, v196
	v_mul_u32_u24_e32 v147, 0x800, v147
	v_lshl_or_b32 v136, v144, 4, v147
	v_add_u32_e32 v137, 0x10000, v136
	v_add_u32_e32 v138, 0x20000, v136
	v_add_u32_e32 v139, 0x30000, v136
	v_and_b32_e32 v144, 15, v196
	v_bfe_u32 v147, v196, 1, 3
	v_xor_b32_e32 v147, v145, v147
	v_lshlrev_b32_e32 v147, 4, v147
	v_xor_b32_e32 v130, 64, v147
	v_lshlrev_b32_e32 v144, 7, v144
	v_lshrrev_b32_e32 v131, 7, v196
	v_lshl_or_b32 v131, v131, 13, v144
	v_lshl_or_b32 v133, v146, 13, v144
	v_add_u32_e32 v140, v131, v147
	v_add_u32_e32 v141, v131, v130
	v_add_u32_e32 v142, v133, v147
	v_add_u32_e32 v143, v133, v130
	v_readfirstlane_b32 s36, v196
	s_lshr_b32 s36, s36, 6
	s_lshl_b32 s36, s36, 10
	s_barrier
	s_add_i32 m0, s36, 0x0
	s_nop 0
	global_load_lds_dwordx4 v136, s[30:31]
	s_add_i32 m0, s36, 0x1000
	s_nop 0
	global_load_lds_dwordx4 v137, s[30:31]
	s_add_i32 m0, s36, 0x2000
	s_nop 0
	global_load_lds_dwordx4 v138, s[30:31]
	s_add_i32 m0, s36, 0x3000
	s_nop 0
	global_load_lds_dwordx4 v139, s[30:31]
	s_add_i32 m0, s36, 0x4000
	s_nop 0
	global_load_lds_dwordx4 v136, s[44:45]
	s_add_i32 m0, s36, 0x5000
	s_nop 0
	global_load_lds_dwordx4 v137, s[44:45]
	s_add_i32 m0, s36, 0x6000
	s_nop 0
	global_load_lds_dwordx4 v138, s[44:45]
	s_add_i32 m0, s36, 0x7000
	s_nop 0
	global_load_lds_dwordx4 v139, s[44:45]
	s_add_u32 s30, s30, 0x80
	s_addc_u32 s31, s31, 0
	s_add_u32 s44, s44, 0x80
	s_addc_u32 s45, s45, 0
	s_add_i32 m0, s36, 0x8000
	s_nop 0
	global_load_lds_dwordx4 v136, s[34:35]
	s_add_i32 m0, s36, 0x9000
	s_nop 0
	global_load_lds_dwordx4 v137, s[34:35]
	s_add_i32 m0, s36, 0xa000
	s_nop 0
	global_load_lds_dwordx4 v138, s[34:35]
	s_add_i32 m0, s36, 0xb000
	s_nop 0
	global_load_lds_dwordx4 v139, s[34:35]
	s_add_u32 s34, s34, 0x80
	s_addc_u32 s35, s35, 0
	v_mov_b64_e32 v[62:63], 0
	v_mov_b64_e32 v[64:65], 0
	v_mov_b64_e32 v[58:59], 0
	v_mov_b64_e32 v[60:61], 0
	v_mov_b64_e32 v[54:55], 0
	v_mov_b64_e32 v[56:57], 0
	v_mov_b64_e32 v[50:51], 0
	v_mov_b64_e32 v[52:53], 0
	v_mov_b64_e32 v[46:47], 0
	v_mov_b64_e32 v[48:49], 0
	v_mov_b64_e32 v[42:43], 0
	v_mov_b64_e32 v[44:45], 0
	v_mov_b64_e32 v[38:39], 0
	v_mov_b64_e32 v[40:41], 0
	v_mov_b64_e32 v[34:35], 0
	v_mov_b64_e32 v[36:37], 0
	v_mov_b64_e32 v[30:31], 0
	v_mov_b64_e32 v[32:33], 0
	v_mov_b64_e32 v[26:27], 0
	v_mov_b64_e32 v[28:29], 0
	v_mov_b64_e32 v[22:23], 0
	v_mov_b64_e32 v[24:25], 0
	v_mov_b64_e32 v[18:19], 0
	v_mov_b64_e32 v[20:21], 0
	v_mov_b64_e32 v[14:15], 0
	v_mov_b64_e32 v[16:17], 0
	v_mov_b64_e32 v[10:11], 0
	v_mov_b64_e32 v[12:13], 0
	v_mov_b64_e32 v[6:7], 0
	v_mov_b64_e32 v[8:9], 0
	v_mov_b64_e32 v[2:3], 0
	v_mov_b64_e32 v[4:5], 0
	v_mov_b64_e32 v[66:67], 0
	v_mov_b64_e32 v[68:69], 0
	v_mov_b64_e32 v[70:71], 0
	v_mov_b64_e32 v[72:73], 0
	v_mov_b64_e32 v[74:75], 0
	v_mov_b64_e32 v[76:77], 0
	v_mov_b64_e32 v[78:79], 0
	v_mov_b64_e32 v[80:81], 0
	v_mov_b64_e32 v[82:83], 0
	v_mov_b64_e32 v[84:85], 0
	v_mov_b64_e32 v[86:87], 0
	v_mov_b64_e32 v[88:89], 0
	v_mov_b64_e32 v[90:91], 0
	v_mov_b64_e32 v[92:93], 0
	v_mov_b64_e32 v[94:95], 0
	v_mov_b64_e32 v[96:97], 0
	v_mov_b64_e32 v[98:99], 0
	v_mov_b64_e32 v[100:101], 0
	v_mov_b64_e32 v[102:103], 0
	v_mov_b64_e32 v[104:105], 0
	v_mov_b64_e32 v[106:107], 0
	v_mov_b64_e32 v[108:109], 0
	v_mov_b64_e32 v[110:111], 0
	v_mov_b64_e32 v[112:113], 0
	v_mov_b64_e32 v[114:115], 0
	v_mov_b64_e32 v[116:117], 0
	v_mov_b64_e32 v[118:119], 0
	v_mov_b64_e32 v[120:121], 0
	v_mov_b64_e32 v[122:123], 0
	v_mov_b64_e32 v[124:125], 0
	v_mov_b64_e32 v[126:127], 0
	v_mov_b64_e32 v[128:129], 0
	s_movk_i32 s37, 7
.Lr2u_k:
	s_waitcnt vmcnt(0)
	s_barrier
	s_add_i32 m0, s36, 0xc000
	s_nop 0
	global_load_lds_dwordx4 v136, s[34:35]
	s_add_i32 m0, s36, 0xd000
	s_nop 0
	global_load_lds_dwordx4 v137, s[34:35]
	s_add_i32 m0, s36, 0xe000
	s_nop 0
	global_load_lds_dwordx4 v138, s[34:35]
	s_add_i32 m0, s36, 0xf000
	s_nop 0
	global_load_lds_dwordx4 v139, s[34:35]
	s_add_u32 s34, s34, 0x80
	s_addc_u32 s35, s35, 0
	ds_read_b128 v[148:151], v140 offset:0
	ds_read_b128 v[152:155], v140 offset:2048
	ds_read_b128 v[156:159], v140 offset:4096
	ds_read_b128 v[160:163], v140 offset:6144
	ds_read_b128 v[164:167], v140 offset:16384
	ds_read_b128 v[168:171], v140 offset:18432
	ds_read_b128 v[174:177], v140 offset:20480
	ds_read_b128 v[182:185], v140 offset:22528
	ds_read_b128 v[188:191], v142 offset:32768
	ds_read_b128 v[192:195], v142 offset:34816
	ds_read_b128 v[208:211], v142 offset:36864
	ds_read_b128 v[212:215], v142 offset:38912
	s_waitcnt lgkmcnt(0)
	s_setprio 1
	v_mfma_f32_16x16x32_bf16 v[62:65], v[188:191], v[148:151], v[62:65]
	v_mfma_f32_16x16x32_bf16 v[58:61], v[192:195], v[148:151], v[58:61]
	v_mfma_f32_16x16x32_bf16 v[54:57], v[208:211], v[148:151], v[54:57]
	v_mfma_f32_16x16x32_bf16 v[50:53], v[212:215], v[148:151], v[50:53]
	v_mfma_f32_16x16x32_bf16 v[46:49], v[188:191], v[152:155], v[46:49]
	v_mfma_f32_16x16x32_bf16 v[42:45], v[192:195], v[152:155], v[42:45]
	v_mfma_f32_16x16x32_bf16 v[38:41], v[208:211], v[152:155], v[38:41]
	v_mfma_f32_16x16x32_bf16 v[34:37], v[212:215], v[152:155], v[34:37]
	v_mfma_f32_16x16x32_bf16 v[30:33], v[188:191], v[156:159], v[30:33]
	v_mfma_f32_16x16x32_bf16 v[26:29], v[192:195], v[156:159], v[26:29]
	v_mfma_f32_16x16x32_bf16 v[22:25], v[208:211], v[156:159], v[22:25]
	v_mfma_f32_16x16x32_bf16 v[18:21], v[212:215], v[156:159], v[18:21]
	v_mfma_f32_16x16x32_bf16 v[14:17], v[188:191], v[160:163], v[14:17]
	v_mfma_f32_16x16x32_bf16 v[10:13], v[192:195], v[160:163], v[10:13]
	v_mfma_f32_16x16x32_bf16 v[6:9], v[208:211], v[160:163], v[6:9]
	v_mfma_f32_16x16x32_bf16 v[2:5], v[212:215], v[160:163], v[2:5]
	v_mfma_f32_16x16x32_bf16 v[66:69], v[188:191], v[164:167], v[66:69]
	v_mfma_f32_16x16x32_bf16 v[70:73], v[192:195], v[164:167], v[70:73]
	v_mfma_f32_16x16x32_bf16 v[74:77], v[208:211], v[164:167], v[74:77]
	v_mfma_f32_16x16x32_bf16 v[78:81], v[212:215], v[164:167], v[78:81]
	v_mfma_f32_16x16x32_bf16 v[82:85], v[188:191], v[168:171], v[82:85]
	v_mfma_f32_16x16x32_bf16 v[86:89], v[192:195], v[168:171], v[86:89]
	v_mfma_f32_16x16x32_bf16 v[90:93], v[208:211], v[168:171], v[90:93]
	v_mfma_f32_16x16x32_bf16 v[94:97], v[212:215], v[168:171], v[94:97]
	v_mfma_f32_16x16x32_bf16 v[98:101], v[188:191], v[174:177], v[98:101]
	v_mfma_f32_16x16x32_bf16 v[102:105], v[192:195], v[174:177], v[102:105]
	v_mfma_f32_16x16x32_bf16 v[106:109], v[208:211], v[174:177], v[106:109]
	v_mfma_f32_16x16x32_bf16 v[110:113], v[212:215], v[174:177], v[110:113]
	v_mfma_f32_16x16x32_bf16 v[114:117], v[188:191], v[182:185], v[114:117]
	v_mfma_f32_16x16x32_bf16 v[118:121], v[192:195], v[182:185], v[118:121]
	v_mfma_f32_16x16x32_bf16 v[122:125], v[208:211], v[182:185], v[122:125]
	v_mfma_f32_16x16x32_bf16 v[126:129], v[212:215], v[182:185], v[126:129]
	s_setprio 0
	ds_read_b128 v[148:151], v141 offset:0
	ds_read_b128 v[152:155], v141 offset:2048
	ds_read_b128 v[156:159], v141 offset:4096
	ds_read_b128 v[160:163], v141 offset:6144
	ds_read_b128 v[164:167], v141 offset:16384
	ds_read_b128 v[168:171], v141 offset:18432
	ds_read_b128 v[174:177], v141 offset:20480
	ds_read_b128 v[182:185], v141 offset:22528
	ds_read_b128 v[188:191], v143 offset:32768
	ds_read_b128 v[192:195], v143 offset:34816
	ds_read_b128 v[208:211], v143 offset:36864
	ds_read_b128 v[212:215], v143 offset:38912
	s_waitcnt lgkmcnt(0)
	s_barrier
	s_add_i32 m0, s36, 0x0
	s_nop 0
	global_load_lds_dwordx4 v136, s[30:31]
	s_add_i32 m0, s36, 0x1000
	s_nop 0
	global_load_lds_dwordx4 v137, s[30:31]
	s_add_i32 m0, s36, 0x2000
	s_nop 0
	global_load_lds_dwordx4 v138, s[30:31]
	s_add_i32 m0, s36, 0x3000
	s_nop 0
	global_load_lds_dwordx4 v139, s[30:31]
	s_add_i32 m0, s36, 0x4000
	s_nop 0
	global_load_lds_dwordx4 v136, s[44:45]
	s_add_i32 m0, s36, 0x5000
	s_nop 0
	global_load_lds_dwordx4 v137, s[44:45]
	s_add_i32 m0, s36, 0x6000
	s_nop 0
	global_load_lds_dwordx4 v138, s[44:45]
	s_add_i32 m0, s36, 0x7000
	s_nop 0
	global_load_lds_dwordx4 v139, s[44:45]
	s_add_u32 s30, s30, 0x80
	s_addc_u32 s31, s31, 0
	s_add_u32 s44, s44, 0x80
	s_addc_u32 s45, s45, 0
	s_setprio 1
	v_mfma_f32_16x16x32_bf16 v[62:65], v[188:191], v[148:151], v[62:65]
	v_mfma_f32_16x16x32_bf16 v[58:61], v[192:195], v[148:151], v[58:61]
	v_mfma_f32_16x16x32_bf16 v[54:57], v[208:211], v[148:151], v[54:57]
	v_mfma_f32_16x16x32_bf16 v[50:53], v[212:215], v[148:151], v[50:53]
	v_mfma_f32_16x16x32_bf16 v[46:49], v[188:191], v[152:155], v[46:49]
	v_mfma_f32_16x16x32_bf16 v[42:45], v[192:195], v[152:155], v[42:45]
	v_mfma_f32_16x16x32_bf16 v[38:41], v[208:211], v[152:155], v[38:41]
	v_mfma_f32_16x16x32_bf16 v[34:37], v[212:215], v[152:155], v[34:37]
	v_mfma_f32_16x16x32_bf16 v[30:33], v[188:191], v[156:159], v[30:33]
	v_mfma_f32_16x16x32_bf16 v[26:29], v[192:195], v[156:159], v[26:29]
	v_mfma_f32_16x16x32_bf16 v[22:25], v[208:211], v[156:159], v[22:25]
	v_mfma_f32_16x16x32_bf16 v[18:21], v[212:215], v[156:159], v[18:21]
	v_mfma_f32_16x16x32_bf16 v[14:17], v[188:191], v[160:163], v[14:17]
	v_mfma_f32_16x16x32_bf16 v[10:13], v[192:195], v[160:163], v[10:13]
	v_mfma_f32_16x16x32_bf16 v[6:9], v[208:211], v[160:163], v[6:9]
	v_mfma_f32_16x16x32_bf16 v[2:5], v[212:215], v[160:163], v[2:5]
	v_mfma_f32_16x16x32_bf16 v[66:69], v[188:191], v[164:167], v[66:69]
	v_mfma_f32_16x16x32_bf16 v[70:73], v[192:195], v[164:167], v[70:73]
	v_mfma_f32_16x16x32_bf16 v[74:77], v[208:211], v[164:167], v[74:77]
	v_mfma_f32_16x16x32_bf16 v[78:81], v[212:215], v[164:167], v[78:81]
	v_mfma_f32_16x16x32_bf16 v[82:85], v[188:191], v[168:171], v[82:85]
	v_mfma_f32_16x16x32_bf16 v[86:89], v[192:195], v[168:171], v[86:89]
	v_mfma_f32_16x16x32_bf16 v[90:93], v[208:211], v[168:171], v[90:93]
	v_mfma_f32_16x16x32_bf16 v[94:97], v[212:215], v[168:171], v[94:97]
	v_mfma_f32_16x16x32_bf16 v[98:101], v[188:191], v[174:177], v[98:101]
	v_mfma_f32_16x16x32_bf16 v[102:105], v[192:195], v[174:177], v[102:105]
	v_mfma_f32_16x16x32_bf16 v[106:109], v[208:211], v[174:177], v[106:109]
	v_mfma_f32_16x16x32_bf16 v[110:113], v[212:215], v[174:177], v[110:113]
	v_mfma_f32_16x16x32_bf16 v[114:117], v[188:191], v[182:185], v[114:117]
	v_mfma_f32_16x16x32_bf16 v[118:121], v[192:195], v[182:185], v[118:121]
	v_mfma_f32_16x16x32_bf16 v[122:125], v[208:211], v[182:185], v[122:125]
	v_mfma_f32_16x16x32_bf16 v[126:129], v[212:215], v[182:185], v[126:129]
	s_setprio 0
	s_waitcnt vmcnt(0)
	s_barrier
	s_add_i32 m0, s36, 0x8000
	s_nop 0
	global_load_lds_dwordx4 v136, s[34:35]
	s_add_i32 m0, s36, 0x9000
	s_nop 0
	global_load_lds_dwordx4 v137, s[34:35]
	s_add_i32 m0, s36, 0xa000
	s_nop 0
	global_load_lds_dwordx4 v138, s[34:35]
	s_add_i32 m0, s36, 0xb000
	s_nop 0
	global_load_lds_dwordx4 v139, s[34:35]
	s_add_u32 s34, s34, 0x80
	s_addc_u32 s35, s35, 0
	ds_read_b128 v[148:151], v140 offset:0
	ds_read_b128 v[152:155], v140 offset:2048
	ds_read_b128 v[156:159], v140 offset:4096
	ds_read_b128 v[160:163], v140 offset:6144
	ds_read_b128 v[164:167], v140 offset:16384
	ds_read_b128 v[168:171], v140 offset:18432
	ds_read_b128 v[174:177], v140 offset:20480
	ds_read_b128 v[182:185], v140 offset:22528
	ds_read_b128 v[188:191], v142 offset:49152
	ds_read_b128 v[192:195], v142 offset:51200
	ds_read_b128 v[208:211], v142 offset:53248
	ds_read_b128 v[212:215], v142 offset:55296
	s_waitcnt lgkmcnt(0)
	s_setprio 1
	v_mfma_f32_16x16x32_bf16 v[62:65], v[188:191], v[148:151], v[62:65]
	v_mfma_f32_16x16x32_bf16 v[58:61], v[192:195], v[148:151], v[58:61]
	v_mfma_f32_16x16x32_bf16 v[54:57], v[208:211], v[148:151], v[54:57]
	v_mfma_f32_16x16x32_bf16 v[50:53], v[212:215], v[148:151], v[50:53]
	v_mfma_f32_16x16x32_bf16 v[46:49], v[188:191], v[152:155], v[46:49]
	v_mfma_f32_16x16x32_bf16 v[42:45], v[192:195], v[152:155], v[42:45]
	v_mfma_f32_16x16x32_bf16 v[38:41], v[208:211], v[152:155], v[38:41]
	v_mfma_f32_16x16x32_bf16 v[34:37], v[212:215], v[152:155], v[34:37]
	v_mfma_f32_16x16x32_bf16 v[30:33], v[188:191], v[156:159], v[30:33]
	v_mfma_f32_16x16x32_bf16 v[26:29], v[192:195], v[156:159], v[26:29]
	v_mfma_f32_16x16x32_bf16 v[22:25], v[208:211], v[156:159], v[22:25]
	v_mfma_f32_16x16x32_bf16 v[18:21], v[212:215], v[156:159], v[18:21]
	v_mfma_f32_16x16x32_bf16 v[14:17], v[188:191], v[160:163], v[14:17]
	v_mfma_f32_16x16x32_bf16 v[10:13], v[192:195], v[160:163], v[10:13]
	v_mfma_f32_16x16x32_bf16 v[6:9], v[208:211], v[160:163], v[6:9]
	v_mfma_f32_16x16x32_bf16 v[2:5], v[212:215], v[160:163], v[2:5]
	v_mfma_f32_16x16x32_bf16 v[66:69], v[188:191], v[164:167], v[66:69]
	v_mfma_f32_16x16x32_bf16 v[70:73], v[192:195], v[164:167], v[70:73]
	v_mfma_f32_16x16x32_bf16 v[74:77], v[208:211], v[164:167], v[74:77]
	v_mfma_f32_16x16x32_bf16 v[78:81], v[212:215], v[164:167], v[78:81]
	v_mfma_f32_16x16x32_bf16 v[82:85], v[188:191], v[168:171], v[82:85]
	v_mfma_f32_16x16x32_bf16 v[86:89], v[192:195], v[168:171], v[86:89]
	v_mfma_f32_16x16x32_bf16 v[90:93], v[208:211], v[168:171], v[90:93]
	v_mfma_f32_16x16x32_bf16 v[94:97], v[212:215], v[168:171], v[94:97]
	v_mfma_f32_16x16x32_bf16 v[98:101], v[188:191], v[174:177], v[98:101]
	v_mfma_f32_16x16x32_bf16 v[102:105], v[192:195], v[174:177], v[102:105]
	v_mfma_f32_16x16x32_bf16 v[106:109], v[208:211], v[174:177], v[106:109]
	v_mfma_f32_16x16x32_bf16 v[110:113], v[212:215], v[174:177], v[110:113]
	v_mfma_f32_16x16x32_bf16 v[114:117], v[188:191], v[182:185], v[114:117]
	v_mfma_f32_16x16x32_bf16 v[118:121], v[192:195], v[182:185], v[118:121]
	v_mfma_f32_16x16x32_bf16 v[122:125], v[208:211], v[182:185], v[122:125]
	v_mfma_f32_16x16x32_bf16 v[126:129], v[212:215], v[182:185], v[126:129]
	s_setprio 0
	ds_read_b128 v[148:151], v141 offset:0
	ds_read_b128 v[152:155], v141 offset:2048
	ds_read_b128 v[156:159], v141 offset:4096
	ds_read_b128 v[160:163], v141 offset:6144
	ds_read_b128 v[164:167], v141 offset:16384
	ds_read_b128 v[168:171], v141 offset:18432
	ds_read_b128 v[174:177], v141 offset:20480
	ds_read_b128 v[182:185], v141 offset:22528
	ds_read_b128 v[188:191], v143 offset:49152
	ds_read_b128 v[192:195], v143 offset:51200
	ds_read_b128 v[208:211], v143 offset:53248
	ds_read_b128 v[212:215], v143 offset:55296
	s_waitcnt lgkmcnt(0)
	s_barrier
	s_add_i32 m0, s36, 0x0
	s_nop 0
	global_load_lds_dwordx4 v136, s[30:31]
	s_add_i32 m0, s36, 0x1000
	s_nop 0
	global_load_lds_dwordx4 v137, s[30:31]
	s_add_i32 m0, s36, 0x2000
	s_nop 0
	global_load_lds_dwordx4 v138, s[30:31]
	s_add_i32 m0, s36, 0x3000
	s_nop 0
	global_load_lds_dwordx4 v139, s[30:31]
	s_add_i32 m0, s36, 0x4000
	s_nop 0
	global_load_lds_dwordx4 v136, s[44:45]
	s_add_i32 m0, s36, 0x5000
	s_nop 0
	global_load_lds_dwordx4 v137, s[44:45]
	s_add_i32 m0, s36, 0x6000
	s_nop 0
	global_load_lds_dwordx4 v138, s[44:45]
	s_add_i32 m0, s36, 0x7000
	s_nop 0
	global_load_lds_dwordx4 v139, s[44:45]
	s_add_u32 s30, s30, 0x80
	s_addc_u32 s31, s31, 0
	s_add_u32 s44, s44, 0x80
	s_addc_u32 s45, s45, 0
	s_setprio 1
	v_mfma_f32_16x16x32_bf16 v[62:65], v[188:191], v[148:151], v[62:65]
	v_mfma_f32_16x16x32_bf16 v[58:61], v[192:195], v[148:151], v[58:61]
	v_mfma_f32_16x16x32_bf16 v[54:57], v[208:211], v[148:151], v[54:57]
	v_mfma_f32_16x16x32_bf16 v[50:53], v[212:215], v[148:151], v[50:53]
	v_mfma_f32_16x16x32_bf16 v[46:49], v[188:191], v[152:155], v[46:49]
	v_mfma_f32_16x16x32_bf16 v[42:45], v[192:195], v[152:155], v[42:45]
	v_mfma_f32_16x16x32_bf16 v[38:41], v[208:211], v[152:155], v[38:41]
	v_mfma_f32_16x16x32_bf16 v[34:37], v[212:215], v[152:155], v[34:37]
	v_mfma_f32_16x16x32_bf16 v[30:33], v[188:191], v[156:159], v[30:33]
	v_mfma_f32_16x16x32_bf16 v[26:29], v[192:195], v[156:159], v[26:29]
	v_mfma_f32_16x16x32_bf16 v[22:25], v[208:211], v[156:159], v[22:25]
	v_mfma_f32_16x16x32_bf16 v[18:21], v[212:215], v[156:159], v[18:21]
	v_mfma_f32_16x16x32_bf16 v[14:17], v[188:191], v[160:163], v[14:17]
	v_mfma_f32_16x16x32_bf16 v[10:13], v[192:195], v[160:163], v[10:13]
	v_mfma_f32_16x16x32_bf16 v[6:9], v[208:211], v[160:163], v[6:9]
	v_mfma_f32_16x16x32_bf16 v[2:5], v[212:215], v[160:163], v[2:5]
	v_mfma_f32_16x16x32_bf16 v[66:69], v[188:191], v[164:167], v[66:69]
	v_mfma_f32_16x16x32_bf16 v[70:73], v[192:195], v[164:167], v[70:73]
	v_mfma_f32_16x16x32_bf16 v[74:77], v[208:211], v[164:167], v[74:77]
	v_mfma_f32_16x16x32_bf16 v[78:81], v[212:215], v[164:167], v[78:81]
	v_mfma_f32_16x16x32_bf16 v[82:85], v[188:191], v[168:171], v[82:85]
	v_mfma_f32_16x16x32_bf16 v[86:89], v[192:195], v[168:171], v[86:89]
	v_mfma_f32_16x16x32_bf16 v[90:93], v[208:211], v[168:171], v[90:93]
	v_mfma_f32_16x16x32_bf16 v[94:97], v[212:215], v[168:171], v[94:97]
	v_mfma_f32_16x16x32_bf16 v[98:101], v[188:191], v[174:177], v[98:101]
	v_mfma_f32_16x16x32_bf16 v[102:105], v[192:195], v[174:177], v[102:105]
	v_mfma_f32_16x16x32_bf16 v[106:109], v[208:211], v[174:177], v[106:109]
	v_mfma_f32_16x16x32_bf16 v[110:113], v[212:215], v[174:177], v[110:113]
	v_mfma_f32_16x16x32_bf16 v[114:117], v[188:191], v[182:185], v[114:117]
	v_mfma_f32_16x16x32_bf16 v[118:121], v[192:195], v[182:185], v[118:121]
	v_mfma_f32_16x16x32_bf16 v[122:125], v[208:211], v[182:185], v[122:125]
	v_mfma_f32_16x16x32_bf16 v[126:129], v[212:215], v[182:185], v[126:129]
	s_setprio 0
	s_add_i32 s37, s37, -1
	s_cmp_lg_u32 s37, 0
	s_cbranch_scc1 .Lr2u_k
	s_waitcnt vmcnt(0)
	s_barrier
	s_add_i32 m0, s36, 0xc000
	s_nop 0
	global_load_lds_dwordx4 v136, s[34:35]
	s_add_i32 m0, s36, 0xd000
	s_nop 0
	global_load_lds_dwordx4 v137, s[34:35]
	s_add_i32 m0, s36, 0xe000
	s_nop 0
	global_load_lds_dwordx4 v138, s[34:35]
	s_add_i32 m0, s36, 0xf000
	s_nop 0
	global_load_lds_dwordx4 v139, s[34:35]
	s_add_u32 s34, s34, 0x80
	s_addc_u32 s35, s35, 0
	ds_read_b128 v[148:151], v140 offset:0
	ds_read_b128 v[152:155], v140 offset:2048
	ds_read_b128 v[156:159], v140 offset:4096
	ds_read_b128 v[160:163], v140 offset:6144
	ds_read_b128 v[164:167], v140 offset:16384
	ds_read_b128 v[168:171], v140 offset:18432
	ds_read_b128 v[174:177], v140 offset:20480
	ds_read_b128 v[182:185], v140 offset:22528
	ds_read_b128 v[188:191], v142 offset:32768
	ds_read_b128 v[192:195], v142 offset:34816
	ds_read_b128 v[208:211], v142 offset:36864
	ds_read_b128 v[212:215], v142 offset:38912
	s_waitcnt lgkmcnt(0)
	s_setprio 1
	v_mfma_f32_16x16x32_bf16 v[62:65], v[188:191], v[148:151], v[62:65]
	v_mfma_f32_16x16x32_bf16 v[58:61], v[192:195], v[148:151], v[58:61]
	v_mfma_f32_16x16x32_bf16 v[54:57], v[208:211], v[148:151], v[54:57]
	v_mfma_f32_16x16x32_bf16 v[50:53], v[212:215], v[148:151], v[50:53]
	v_mfma_f32_16x16x32_bf16 v[46:49], v[188:191], v[152:155], v[46:49]
	v_mfma_f32_16x16x32_bf16 v[42:45], v[192:195], v[152:155], v[42:45]
	v_mfma_f32_16x16x32_bf16 v[38:41], v[208:211], v[152:155], v[38:41]
	v_mfma_f32_16x16x32_bf16 v[34:37], v[212:215], v[152:155], v[34:37]
	v_mfma_f32_16x16x32_bf16 v[30:33], v[188:191], v[156:159], v[30:33]
	v_mfma_f32_16x16x32_bf16 v[26:29], v[192:195], v[156:159], v[26:29]
	v_mfma_f32_16x16x32_bf16 v[22:25], v[208:211], v[156:159], v[22:25]
	v_mfma_f32_16x16x32_bf16 v[18:21], v[212:215], v[156:159], v[18:21]
	v_mfma_f32_16x16x32_bf16 v[14:17], v[188:191], v[160:163], v[14:17]
	v_mfma_f32_16x16x32_bf16 v[10:13], v[192:195], v[160:163], v[10:13]
	v_mfma_f32_16x16x32_bf16 v[6:9], v[208:211], v[160:163], v[6:9]
	v_mfma_f32_16x16x32_bf16 v[2:5], v[212:215], v[160:163], v[2:5]
	v_mfma_f32_16x16x32_bf16 v[66:69], v[188:191], v[164:167], v[66:69]
	v_mfma_f32_16x16x32_bf16 v[70:73], v[192:195], v[164:167], v[70:73]
	v_mfma_f32_16x16x32_bf16 v[74:77], v[208:211], v[164:167], v[74:77]
	v_mfma_f32_16x16x32_bf16 v[78:81], v[212:215], v[164:167], v[78:81]
	v_mfma_f32_16x16x32_bf16 v[82:85], v[188:191], v[168:171], v[82:85]
	v_mfma_f32_16x16x32_bf16 v[86:89], v[192:195], v[168:171], v[86:89]
	v_mfma_f32_16x16x32_bf16 v[90:93], v[208:211], v[168:171], v[90:93]
	v_mfma_f32_16x16x32_bf16 v[94:97], v[212:215], v[168:171], v[94:97]
	v_mfma_f32_16x16x32_bf16 v[98:101], v[188:191], v[174:177], v[98:101]
	v_mfma_f32_16x16x32_bf16 v[102:105], v[192:195], v[174:177], v[102:105]
	v_mfma_f32_16x16x32_bf16 v[106:109], v[208:211], v[174:177], v[106:109]
	v_mfma_f32_16x16x32_bf16 v[110:113], v[212:215], v[174:177], v[110:113]
	v_mfma_f32_16x16x32_bf16 v[114:117], v[188:191], v[182:185], v[114:117]
	v_mfma_f32_16x16x32_bf16 v[118:121], v[192:195], v[182:185], v[118:121]
	v_mfma_f32_16x16x32_bf16 v[122:125], v[208:211], v[182:185], v[122:125]
	v_mfma_f32_16x16x32_bf16 v[126:129], v[212:215], v[182:185], v[126:129]
	s_setprio 0
	ds_read_b128 v[148:151], v141 offset:0
	ds_read_b128 v[152:155], v141 offset:2048
	ds_read_b128 v[156:159], v141 offset:4096
	ds_read_b128 v[160:163], v141 offset:6144
	ds_read_b128 v[164:167], v141 offset:16384
	ds_read_b128 v[168:171], v141 offset:18432
	ds_read_b128 v[174:177], v141 offset:20480
	ds_read_b128 v[182:185], v141 offset:22528
	ds_read_b128 v[188:191], v143 offset:32768
	ds_read_b128 v[192:195], v143 offset:34816
	ds_read_b128 v[208:211], v143 offset:36864
	ds_read_b128 v[212:215], v143 offset:38912
	s_waitcnt lgkmcnt(0)
	s_barrier
	s_add_i32 m0, s36, 0x0
	s_nop 0
	global_load_lds_dwordx4 v136, s[30:31]
	s_add_i32 m0, s36, 0x1000
	s_nop 0
	global_load_lds_dwordx4 v137, s[30:31]
	s_add_i32 m0, s36, 0x2000
	s_nop 0
	global_load_lds_dwordx4 v138, s[30:31]
	s_add_i32 m0, s36, 0x3000
	s_nop 0
	global_load_lds_dwordx4 v139, s[30:31]
	s_add_i32 m0, s36, 0x4000
	s_nop 0
	global_load_lds_dwordx4 v136, s[44:45]
	s_add_i32 m0, s36, 0x5000
	s_nop 0
	global_load_lds_dwordx4 v137, s[44:45]
	s_add_i32 m0, s36, 0x6000
	s_nop 0
	global_load_lds_dwordx4 v138, s[44:45]
	s_add_i32 m0, s36, 0x7000
	s_nop 0
	global_load_lds_dwordx4 v139, s[44:45]
	s_add_u32 s30, s30, 0x80
	s_addc_u32 s31, s31, 0
	s_add_u32 s44, s44, 0x80
	s_addc_u32 s45, s45, 0
	s_setprio 1
	v_mfma_f32_16x16x32_bf16 v[62:65], v[188:191], v[148:151], v[62:65]
	v_mfma_f32_16x16x32_bf16 v[58:61], v[192:195], v[148:151], v[58:61]
	v_mfma_f32_16x16x32_bf16 v[54:57], v[208:211], v[148:151], v[54:57]
	v_mfma_f32_16x16x32_bf16 v[50:53], v[212:215], v[148:151], v[50:53]
	v_mfma_f32_16x16x32_bf16 v[46:49], v[188:191], v[152:155], v[46:49]
	v_mfma_f32_16x16x32_bf16 v[42:45], v[192:195], v[152:155], v[42:45]
	v_mfma_f32_16x16x32_bf16 v[38:41], v[208:211], v[152:155], v[38:41]
	v_mfma_f32_16x16x32_bf16 v[34:37], v[212:215], v[152:155], v[34:37]
	v_mfma_f32_16x16x32_bf16 v[30:33], v[188:191], v[156:159], v[30:33]
	v_mfma_f32_16x16x32_bf16 v[26:29], v[192:195], v[156:159], v[26:29]
	v_mfma_f32_16x16x32_bf16 v[22:25], v[208:211], v[156:159], v[22:25]
	v_mfma_f32_16x16x32_bf16 v[18:21], v[212:215], v[156:159], v[18:21]
	v_mfma_f32_16x16x32_bf16 v[14:17], v[188:191], v[160:163], v[14:17]
	v_mfma_f32_16x16x32_bf16 v[10:13], v[192:195], v[160:163], v[10:13]
	v_mfma_f32_16x16x32_bf16 v[6:9], v[208:211], v[160:163], v[6:9]
	v_mfma_f32_16x16x32_bf16 v[2:5], v[212:215], v[160:163], v[2:5]
	v_mfma_f32_16x16x32_bf16 v[66:69], v[188:191], v[164:167], v[66:69]
	v_mfma_f32_16x16x32_bf16 v[70:73], v[192:195], v[164:167], v[70:73]
	v_mfma_f32_16x16x32_bf16 v[74:77], v[208:211], v[164:167], v[74:77]
	v_mfma_f32_16x16x32_bf16 v[78:81], v[212:215], v[164:167], v[78:81]
	v_mfma_f32_16x16x32_bf16 v[82:85], v[188:191], v[168:171], v[82:85]
	v_mfma_f32_16x16x32_bf16 v[86:89], v[192:195], v[168:171], v[86:89]
	v_mfma_f32_16x16x32_bf16 v[90:93], v[208:211], v[168:171], v[90:93]
	v_mfma_f32_16x16x32_bf16 v[94:97], v[212:215], v[168:171], v[94:97]
	v_mfma_f32_16x16x32_bf16 v[98:101], v[188:191], v[174:177], v[98:101]
	v_mfma_f32_16x16x32_bf16 v[102:105], v[192:195], v[174:177], v[102:105]
	v_mfma_f32_16x16x32_bf16 v[106:109], v[208:211], v[174:177], v[106:109]
	v_mfma_f32_16x16x32_bf16 v[110:113], v[212:215], v[174:177], v[110:113]
	v_mfma_f32_16x16x32_bf16 v[114:117], v[188:191], v[182:185], v[114:117]
	v_mfma_f32_16x16x32_bf16 v[118:121], v[192:195], v[182:185], v[118:121]
	v_mfma_f32_16x16x32_bf16 v[122:125], v[208:211], v[182:185], v[122:125]
	v_mfma_f32_16x16x32_bf16 v[126:129], v[212:215], v[182:185], v[126:129]
	s_setprio 0
	s_waitcnt vmcnt(0)
	s_barrier
	ds_read_b128 v[148:151], v140 offset:0
	ds_read_b128 v[152:155], v140 offset:2048
	ds_read_b128 v[156:159], v140 offset:4096
	ds_read_b128 v[160:163], v140 offset:6144
	ds_read_b128 v[164:167], v140 offset:16384
	ds_read_b128 v[168:171], v140 offset:18432
	ds_read_b128 v[174:177], v140 offset:20480
	ds_read_b128 v[182:185], v140 offset:22528
	ds_read_b128 v[188:191], v142 offset:49152
	ds_read_b128 v[192:195], v142 offset:51200
	ds_read_b128 v[208:211], v142 offset:53248
	ds_read_b128 v[212:215], v142 offset:55296
	s_waitcnt lgkmcnt(0)
	s_setprio 1
	v_mfma_f32_16x16x32_bf16 v[62:65], v[188:191], v[148:151], v[62:65]
	v_mfma_f32_16x16x32_bf16 v[58:61], v[192:195], v[148:151], v[58:61]
	v_mfma_f32_16x16x32_bf16 v[54:57], v[208:211], v[148:151], v[54:57]
	v_mfma_f32_16x16x32_bf16 v[50:53], v[212:215], v[148:151], v[50:53]
	v_mfma_f32_16x16x32_bf16 v[46:49], v[188:191], v[152:155], v[46:49]
	v_mfma_f32_16x16x32_bf16 v[42:45], v[192:195], v[152:155], v[42:45]
	v_mfma_f32_16x16x32_bf16 v[38:41], v[208:211], v[152:155], v[38:41]
	v_mfma_f32_16x16x32_bf16 v[34:37], v[212:215], v[152:155], v[34:37]
	v_mfma_f32_16x16x32_bf16 v[30:33], v[188:191], v[156:159], v[30:33]
	v_mfma_f32_16x16x32_bf16 v[26:29], v[192:195], v[156:159], v[26:29]
	v_mfma_f32_16x16x32_bf16 v[22:25], v[208:211], v[156:159], v[22:25]
	v_mfma_f32_16x16x32_bf16 v[18:21], v[212:215], v[156:159], v[18:21]
	v_mfma_f32_16x16x32_bf16 v[14:17], v[188:191], v[160:163], v[14:17]
	v_mfma_f32_16x16x32_bf16 v[10:13], v[192:195], v[160:163], v[10:13]
	v_mfma_f32_16x16x32_bf16 v[6:9], v[208:211], v[160:163], v[6:9]
	v_mfma_f32_16x16x32_bf16 v[2:5], v[212:215], v[160:163], v[2:5]
	v_mfma_f32_16x16x32_bf16 v[66:69], v[188:191], v[164:167], v[66:69]
	v_mfma_f32_16x16x32_bf16 v[70:73], v[192:195], v[164:167], v[70:73]
	v_mfma_f32_16x16x32_bf16 v[74:77], v[208:211], v[164:167], v[74:77]
	v_mfma_f32_16x16x32_bf16 v[78:81], v[212:215], v[164:167], v[78:81]
	v_mfma_f32_16x16x32_bf16 v[82:85], v[188:191], v[168:171], v[82:85]
	v_mfma_f32_16x16x32_bf16 v[86:89], v[192:195], v[168:171], v[86:89]
	v_mfma_f32_16x16x32_bf16 v[90:93], v[208:211], v[168:171], v[90:93]
	v_mfma_f32_16x16x32_bf16 v[94:97], v[212:215], v[168:171], v[94:97]
	v_mfma_f32_16x16x32_bf16 v[98:101], v[188:191], v[174:177], v[98:101]
	v_mfma_f32_16x16x32_bf16 v[102:105], v[192:195], v[174:177], v[102:105]
	v_mfma_f32_16x16x32_bf16 v[106:109], v[208:211], v[174:177], v[106:109]
	v_mfma_f32_16x16x32_bf16 v[110:113], v[212:215], v[174:177], v[110:113]
	v_mfma_f32_16x16x32_bf16 v[114:117], v[188:191], v[182:185], v[114:117]
	v_mfma_f32_16x16x32_bf16 v[118:121], v[192:195], v[182:185], v[118:121]
	v_mfma_f32_16x16x32_bf16 v[122:125], v[208:211], v[182:185], v[122:125]
	v_mfma_f32_16x16x32_bf16 v[126:129], v[212:215], v[182:185], v[126:129]
	s_setprio 0
	ds_read_b128 v[148:151], v141 offset:0
	ds_read_b128 v[152:155], v141 offset:2048
	ds_read_b128 v[156:159], v141 offset:4096
	ds_read_b128 v[160:163], v141 offset:6144
	ds_read_b128 v[164:167], v141 offset:16384
	ds_read_b128 v[168:171], v141 offset:18432
	ds_read_b128 v[174:177], v141 offset:20480
	ds_read_b128 v[182:185], v141 offset:22528
	ds_read_b128 v[188:191], v143 offset:49152
	ds_read_b128 v[192:195], v143 offset:51200
	ds_read_b128 v[208:211], v143 offset:53248
	ds_read_b128 v[212:215], v143 offset:55296
	s_waitcnt lgkmcnt(0)
	s_setprio 1
	v_mfma_f32_16x16x32_bf16 v[62:65], v[188:191], v[148:151], v[62:65]
	v_mfma_f32_16x16x32_bf16 v[58:61], v[192:195], v[148:151], v[58:61]
	v_mfma_f32_16x16x32_bf16 v[54:57], v[208:211], v[148:151], v[54:57]
	v_mfma_f32_16x16x32_bf16 v[50:53], v[212:215], v[148:151], v[50:53]
	v_mfma_f32_16x16x32_bf16 v[46:49], v[188:191], v[152:155], v[46:49]
	v_mfma_f32_16x16x32_bf16 v[42:45], v[192:195], v[152:155], v[42:45]
	v_mfma_f32_16x16x32_bf16 v[38:41], v[208:211], v[152:155], v[38:41]
	v_mfma_f32_16x16x32_bf16 v[34:37], v[212:215], v[152:155], v[34:37]
	v_mfma_f32_16x16x32_bf16 v[30:33], v[188:191], v[156:159], v[30:33]
	v_mfma_f32_16x16x32_bf16 v[26:29], v[192:195], v[156:159], v[26:29]
	v_mfma_f32_16x16x32_bf16 v[22:25], v[208:211], v[156:159], v[22:25]
	v_mfma_f32_16x16x32_bf16 v[18:21], v[212:215], v[156:159], v[18:21]
	v_mfma_f32_16x16x32_bf16 v[14:17], v[188:191], v[160:163], v[14:17]
	v_mfma_f32_16x16x32_bf16 v[10:13], v[192:195], v[160:163], v[10:13]
	v_mfma_f32_16x16x32_bf16 v[6:9], v[208:211], v[160:163], v[6:9]
	v_mfma_f32_16x16x32_bf16 v[2:5], v[212:215], v[160:163], v[2:5]
	v_mfma_f32_16x16x32_bf16 v[66:69], v[188:191], v[164:167], v[66:69]
	v_mfma_f32_16x16x32_bf16 v[70:73], v[192:195], v[164:167], v[70:73]
	v_mfma_f32_16x16x32_bf16 v[74:77], v[208:211], v[164:167], v[74:77]
	v_mfma_f32_16x16x32_bf16 v[78:81], v[212:215], v[164:167], v[78:81]
	v_mfma_f32_16x16x32_bf16 v[82:85], v[188:191], v[168:171], v[82:85]
	v_mfma_f32_16x16x32_bf16 v[86:89], v[192:195], v[168:171], v[86:89]
	v_mfma_f32_16x16x32_bf16 v[90:93], v[208:211], v[168:171], v[90:93]
	v_mfma_f32_16x16x32_bf16 v[94:97], v[212:215], v[168:171], v[94:97]
	v_mfma_f32_16x16x32_bf16 v[98:101], v[188:191], v[174:177], v[98:101]
	v_mfma_f32_16x16x32_bf16 v[102:105], v[192:195], v[174:177], v[102:105]
	v_mfma_f32_16x16x32_bf16 v[106:109], v[208:211], v[174:177], v[106:109]
	v_mfma_f32_16x16x32_bf16 v[110:113], v[212:215], v[174:177], v[110:113]
	v_mfma_f32_16x16x32_bf16 v[114:117], v[188:191], v[182:185], v[114:117]
	v_mfma_f32_16x16x32_bf16 v[118:121], v[192:195], v[182:185], v[118:121]
	v_mfma_f32_16x16x32_bf16 v[122:125], v[208:211], v[182:185], v[122:125]
	v_mfma_f32_16x16x32_bf16 v[126:129], v[212:215], v[182:185], v[126:129]
	s_setprio 0
	v_lshrrev_b32_e32 v144, 7, v196
	v_and_b32_e32 v145, 15, v196
	v_lshl_or_b32 v144, v144, 6, v145
	v_lshlrev_b32_e32 v144, 12, v144
	v_bfe_u32 v145, v196, 6, 1
	v_bfe_u32 v146, v196, 4, 2
	v_lshlrev_b32_e32 v145, 8, v145
	v_lshl_or_b32 v145, v146, 4, v145
	v_add_u32_e32 v136, v144, v145
	v_add_u32_e32 v137, 0x10000, v136
	v_add_u32_e32 v138, 0x20000, v136
	v_add_u32_e32 v139, 0x30000, v136
	s_nop 7
	s_nop 7
	s_nop 7
	global_load_dwordx4 v[148:151], v136, s[50:51] offset:0
	global_load_dwordx4 v[152:155], v136, s[50:51] offset:64
	global_load_dwordx4 v[156:159], v136, s[50:51] offset:128
	global_load_dwordx4 v[160:163], v136, s[50:51] offset:192
	global_load_dwordx4 v[164:167], v137, s[50:51] offset:0
	global_load_dwordx4 v[168:171], v137, s[50:51] offset:64
	global_load_dwordx4 v[174:177], v137, s[50:51] offset:128
	global_load_dwordx4 v[182:185], v137, s[50:51] offset:192
	global_load_dwordx4 v[188:191], v138, s[50:51] offset:0
	global_load_dwordx4 v[192:195], v138, s[50:51] offset:64
	global_load_dwordx4 v[208:211], v138, s[50:51] offset:128
	global_load_dwordx4 v[212:215], v138, s[50:51] offset:192
	global_load_dwordx4 v[216:219], v139, s[50:51] offset:0
	global_load_dwordx4 v[220:223], v139, s[50:51] offset:64
	global_load_dwordx4 v[242:245], v139, s[50:51] offset:128
	global_load_dwordx4 v[144:147], v139, s[50:51] offset:192
	s_waitcnt vmcnt(0)
	v_pk_add_f32 v[62:63], v[62:63], v[148:149]
	v_pk_add_f32 v[64:65], v[64:65], v[150:151]
	v_pk_add_f32 v[58:59], v[58:59], v[152:153]
	v_pk_add_f32 v[60:61], v[60:61], v[154:155]
	v_pk_add_f32 v[54:55], v[54:55], v[156:157]
	v_pk_add_f32 v[56:57], v[56:57], v[158:159]
	v_pk_add_f32 v[50:51], v[50:51], v[160:161]
	v_pk_add_f32 v[52:53], v[52:53], v[162:163]
	v_pk_add_f32 v[46:47], v[46:47], v[164:165]
	v_pk_add_f32 v[48:49], v[48:49], v[166:167]
	v_pk_add_f32 v[42:43], v[42:43], v[168:169]
	v_pk_add_f32 v[44:45], v[44:45], v[170:171]
	v_pk_add_f32 v[38:39], v[38:39], v[174:175]
	v_pk_add_f32 v[40:41], v[40:41], v[176:177]
	v_pk_add_f32 v[34:35], v[34:35], v[182:183]
	v_pk_add_f32 v[36:37], v[36:37], v[184:185]
	v_pk_add_f32 v[30:31], v[30:31], v[188:189]
	v_pk_add_f32 v[32:33], v[32:33], v[190:191]
	v_pk_add_f32 v[26:27], v[26:27], v[192:193]
	v_pk_add_f32 v[28:29], v[28:29], v[194:195]
	v_pk_add_f32 v[22:23], v[22:23], v[208:209]
	v_pk_add_f32 v[24:25], v[24:25], v[210:211]
	v_pk_add_f32 v[18:19], v[18:19], v[212:213]
	v_pk_add_f32 v[20:21], v[20:21], v[214:215]
	v_pk_add_f32 v[14:15], v[14:15], v[216:217]
	v_pk_add_f32 v[16:17], v[16:17], v[218:219]
	v_pk_add_f32 v[10:11], v[10:11], v[220:221]
	v_pk_add_f32 v[12:13], v[12:13], v[222:223]
	v_pk_add_f32 v[6:7], v[6:7], v[242:243]
	v_pk_add_f32 v[8:9], v[8:9], v[244:245]
	v_pk_add_f32 v[2:3], v[2:3], v[144:145]
	v_pk_add_f32 v[4:5], v[4:5], v[146:147]
	global_load_dwordx4 v[148:151], v136, s[52:53] offset:0
	global_load_dwordx4 v[152:155], v136, s[52:53] offset:64
	global_load_dwordx4 v[156:159], v136, s[52:53] offset:128
	global_load_dwordx4 v[160:163], v136, s[52:53] offset:192
	global_load_dwordx4 v[164:167], v137, s[52:53] offset:0
	global_load_dwordx4 v[168:171], v137, s[52:53] offset:64
	global_load_dwordx4 v[174:177], v137, s[52:53] offset:128
	global_load_dwordx4 v[182:185], v137, s[52:53] offset:192
	global_load_dwordx4 v[188:191], v138, s[52:53] offset:0
	global_load_dwordx4 v[192:195], v138, s[52:53] offset:64
	global_load_dwordx4 v[208:211], v138, s[52:53] offset:128
	global_load_dwordx4 v[212:215], v138, s[52:53] offset:192
	global_load_dwordx4 v[216:219], v139, s[52:53] offset:0
	global_load_dwordx4 v[220:223], v139, s[52:53] offset:64
	global_load_dwordx4 v[242:245], v139, s[52:53] offset:128
	global_load_dwordx4 v[144:147], v139, s[52:53] offset:192
	global_store_dwordx4 v136, v[62:65], s[40:41] offset:0
	global_store_dwordx4 v136, v[58:61], s[40:41] offset:64
	global_store_dwordx4 v136, v[54:57], s[40:41] offset:128
	global_store_dwordx4 v136, v[50:53], s[40:41] offset:192
	global_store_dwordx4 v137, v[46:49], s[40:41] offset:0
	global_store_dwordx4 v137, v[42:45], s[40:41] offset:64
	global_store_dwordx4 v137, v[38:41], s[40:41] offset:128
	global_store_dwordx4 v137, v[34:37], s[40:41] offset:192
	global_store_dwordx4 v138, v[30:33], s[40:41] offset:0
	global_store_dwordx4 v138, v[26:29], s[40:41] offset:64
	global_store_dwordx4 v138, v[22:25], s[40:41] offset:128
	global_store_dwordx4 v138, v[18:21], s[40:41] offset:192
	global_store_dwordx4 v139, v[14:17], s[40:41] offset:0
	global_store_dwordx4 v139, v[10:13], s[40:41] offset:64
	global_store_dwordx4 v139, v[6:9], s[40:41] offset:128
	global_store_dwordx4 v139, v[2:5], s[40:41] offset:192
	s_waitcnt vmcnt(0)
	v_pk_add_f32 v[66:67], v[66:67], v[148:149]
	v_pk_add_f32 v[68:69], v[68:69], v[150:151]
	v_pk_add_f32 v[70:71], v[70:71], v[152:153]
	v_pk_add_f32 v[72:73], v[72:73], v[154:155]
	v_pk_add_f32 v[74:75], v[74:75], v[156:157]
	v_pk_add_f32 v[76:77], v[76:77], v[158:159]
	v_pk_add_f32 v[78:79], v[78:79], v[160:161]
	v_pk_add_f32 v[80:81], v[80:81], v[162:163]
	v_pk_add_f32 v[82:83], v[82:83], v[164:165]
	v_pk_add_f32 v[84:85], v[84:85], v[166:167]
	v_pk_add_f32 v[86:87], v[86:87], v[168:169]
	v_pk_add_f32 v[88:89], v[88:89], v[170:171]
	v_pk_add_f32 v[90:91], v[90:91], v[174:175]
	v_pk_add_f32 v[92:93], v[92:93], v[176:177]
	v_pk_add_f32 v[94:95], v[94:95], v[182:183]
	v_pk_add_f32 v[96:97], v[96:97], v[184:185]
	v_pk_add_f32 v[98:99], v[98:99], v[188:189]
	v_pk_add_f32 v[100:101], v[100:101], v[190:191]
	v_pk_add_f32 v[102:103], v[102:103], v[192:193]
	v_pk_add_f32 v[104:105], v[104:105], v[194:195]
	v_pk_add_f32 v[106:107], v[106:107], v[208:209]
	v_pk_add_f32 v[108:109], v[108:109], v[210:211]
	v_pk_add_f32 v[110:111], v[110:111], v[212:213]
	v_pk_add_f32 v[112:113], v[112:113], v[214:215]
	v_pk_add_f32 v[114:115], v[114:115], v[216:217]
	v_pk_add_f32 v[116:117], v[116:117], v[218:219]
	v_pk_add_f32 v[118:119], v[118:119], v[220:221]
	v_pk_add_f32 v[120:121], v[120:121], v[222:223]
	v_pk_add_f32 v[122:123], v[122:123], v[242:243]
	v_pk_add_f32 v[124:125], v[124:125], v[244:245]
	v_pk_add_f32 v[126:127], v[126:127], v[144:145]
	v_pk_add_f32 v[128:129], v[128:129], v[146:147]
	global_store_dwordx4 v136, v[66:69], s[42:43] offset:0
	global_store_dwordx4 v136, v[70:73], s[42:43] offset:64
	global_store_dwordx4 v136, v[74:77], s[42:43] offset:128
	global_store_dwordx4 v136, v[78:81], s[42:43] offset:192
	global_store_dwordx4 v137, v[82:85], s[42:43] offset:0
	global_store_dwordx4 v137, v[86:89], s[42:43] offset:64
	global_store_dwordx4 v137, v[90:93], s[42:43] offset:128
	global_store_dwordx4 v137, v[94:97], s[42:43] offset:192
	global_store_dwordx4 v138, v[98:101], s[42:43] offset:0
	global_store_dwordx4 v138, v[102:105], s[42:43] offset:64
	global_store_dwordx4 v138, v[106:109], s[42:43] offset:128
	global_store_dwordx4 v138, v[110:113], s[42:43] offset:192
	global_store_dwordx4 v139, v[114:117], s[42:43] offset:0
	global_store_dwordx4 v139, v[118:121], s[42:43] offset:64
	global_store_dwordx4 v139, v[122:125], s[42:43] offset:128
	global_store_dwordx4 v139, v[126:129], s[42:43] offset:192
	s_branch .LBB0_2211
